# P3 k-loop: the group-B hook test (4 branches between the last MFMA and the loop-back barrier) replaced by SALU interleaved in the last MFMA cluster plus one branch
# speedup vs baseline: 1.0058x; 1.0035x over previous
.Lpeel_mid_p3:
	s_add_i32 s75, 0, 0x18000
	v_add_u32_e32 v1, s75, v173
	s_add_i32 s91, 0, 0x1c000
	ds_read_b128 v[132:135], v1
	ds_read_b128 v[136:139], v1 offset:1024
	ds_read_b128 v[140:143], v1 offset:2048
	ds_read_b128 v[178:181], v1 offset:3072
	v_add_u32_e32 v1, s91, v173
	ds_read_b128 v[182:185], v1
	ds_read_b128 v[188:191], v1 offset:1024
	ds_read_b128 v[192:195], v1 offset:2048
	ds_read_b128 v[196:199], v1 offset:3072
	s_add_u32 s66, s66, 0xa0000
	s_addc_u32 s67, s67, 0
	s_mov_b32 m0, s71
	v_lshl_add_u64 v[6:7], s[66:67], 0, v[150:151]
	ds_read_b128 v[200:203], v174 offset:32768
	ds_read_b128 v[204:207], v174 offset:33792
	ds_read_b128 v[208:211], v174 offset:34816
	ds_read_b128 v[212:215], v174 offset:35840
	ds_read_b128 v[216:219], v174 offset:36864
	ds_read_b128 v[220:223], v174 offset:37888
	ds_read_b128 v[224:227], v174 offset:38912
	ds_read_b128 v[228:231], v174 offset:39936
	global_load_lds_dwordx4 v[6:7], off
	v_lshl_add_u64 v[6:7], s[66:67], 0, v[146:147]
	s_mov_b32 m0, s72
	s_nop 0
	global_load_lds_dwordx4 v[6:7], off
	s_waitcnt vmcnt(8)
	s_waitcnt lgkmcnt(0)
	s_waitcnt lgkmcnt(0)
	s_setprio 1
	s_barrier
	v_mfma_f32_16x16x32_bf16 v[128:131], v[132:135], v[200:203], v[128:131]
	v_mfma_f32_16x16x32_bf16 v[124:127], v[140:143], v[200:203], v[124:127]
	v_mfma_f32_16x16x32_bf16 v[112:115], v[132:135], v[208:211], v[112:115]
	v_mfma_f32_16x16x32_bf16 v[108:111], v[140:143], v[208:211], v[108:111]
	v_mfma_f32_16x16x32_bf16 v[96:99], v[132:135], v[216:219], v[96:99]
	v_mfma_f32_16x16x32_bf16 v[92:95], v[140:143], v[216:219], v[92:95]
	v_mfma_f32_16x16x32_bf16 v[80:83], v[132:135], v[224:227], v[80:83]
	v_mfma_f32_16x16x32_bf16 v[76:79], v[140:143], v[224:227], v[76:79]
	v_mfma_f32_16x16x32_bf16 v[128:131], v[136:139], v[204:207], v[128:131]
	v_mfma_f32_16x16x32_bf16 v[124:127], v[178:181], v[204:207], v[124:127]
	v_mfma_f32_16x16x32_bf16 v[112:115], v[136:139], v[212:215], v[112:115]
	v_mfma_f32_16x16x32_bf16 v[108:111], v[178:181], v[212:215], v[108:111]
	v_mfma_f32_16x16x32_bf16 v[96:99], v[136:139], v[220:223], v[96:99]
	v_mfma_f32_16x16x32_bf16 v[92:95], v[178:181], v[220:223], v[92:95]
	v_mfma_f32_16x16x32_bf16 v[80:83], v[136:139], v[228:231], v[80:83]
	v_mfma_f32_16x16x32_bf16 v[76:79], v[178:181], v[228:231], v[76:79]
	s_setprio 0
	s_setprio 1
	v_mfma_f32_16x16x32_bf16 v[120:123], v[182:185], v[200:203], v[120:123]
	v_mfma_f32_16x16x32_bf16 v[116:119], v[192:195], v[200:203], v[116:119]
	v_mfma_f32_16x16x32_bf16 v[104:107], v[182:185], v[208:211], v[104:107]
	v_mfma_f32_16x16x32_bf16 v[100:103], v[192:195], v[208:211], v[100:103]
	v_mfma_f32_16x16x32_bf16 v[88:91], v[182:185], v[216:219], v[88:91]
	v_mfma_f32_16x16x32_bf16 v[84:87], v[192:195], v[216:219], v[84:87]
	v_mfma_f32_16x16x32_bf16 v[72:75], v[182:185], v[224:227], v[72:75]
	v_mfma_f32_16x16x32_bf16 v[68:71], v[192:195], v[224:227], v[68:71]
	v_mfma_f32_16x16x32_bf16 v[120:123], v[188:191], v[204:207], v[120:123]
	v_mfma_f32_16x16x32_bf16 v[116:119], v[196:199], v[204:207], v[116:119]
	v_mfma_f32_16x16x32_bf16 v[104:107], v[188:191], v[212:215], v[104:107]
	v_mfma_f32_16x16x32_bf16 v[100:103], v[196:199], v[212:215], v[100:103]
	v_mfma_f32_16x16x32_bf16 v[88:91], v[188:191], v[220:223], v[88:91]
	v_mfma_f32_16x16x32_bf16 v[84:87], v[196:199], v[220:223], v[84:87]
	v_mfma_f32_16x16x32_bf16 v[72:75], v[188:191], v[228:231], v[72:75]
	v_mfma_f32_16x16x32_bf16 v[68:71], v[196:199], v[228:231], v[68:71]
	s_barrier
	s_setprio 0
	s_add_i32 s66, s75, s68
	v_lshl_add_u64 v[6:7], v[232:233], 0, s[14:15]
	s_mov_b32 m0, s66
	ds_read_b128 v[200:203], v174 offset:49152
	ds_read_b128 v[204:207], v174 offset:50176
	ds_read_b128 v[208:211], v174 offset:51200
	ds_read_b128 v[212:215], v174 offset:52224
	ds_read_b128 v[216:219], v174 offset:53248
	ds_read_b128 v[220:223], v174 offset:54272
	ds_read_b128 v[224:227], v174 offset:55296
	ds_read_b128 v[228:231], v174 offset:56320
	global_load_lds_dwordx4 v[6:7], off
	s_add_i32 m0, s66, 0x2000
	s_add_u32 s64, s64, 0xa0080
	v_lshl_add_u64 v[6:7], v[234:235], 0, s[14:15]
	s_addc_u32 s65, s65, 0
	s_add_i32 s66, s91, s68
	global_load_lds_dwordx4 v[6:7], off
	v_lshl_add_u64 v[6:7], s[64:65], 0, v[148:149]
	s_mov_b32 m0, s66
	s_nop 0
	global_load_lds_dwordx4 v[6:7], off
	v_lshl_add_u64 v[6:7], s[64:65], 0, v[144:145]
	s_add_i32 m0, s66, 0x2000
	s_nop 0
	global_load_lds_dwordx4 v[6:7], off
	v_lshl_add_u64 v[6:7], v[236:237], 0, s[14:15]
	s_mov_b32 m0, s73
	s_nop 0
	global_load_lds_dwordx4 v[6:7], off
	v_lshl_add_u64 v[6:7], v[238:239], 0, s[14:15]
	s_mov_b32 m0, s76
	s_nop 0
	global_load_lds_dwordx4 v[6:7], off
	s_waitcnt vmcnt(8)
	s_waitcnt lgkmcnt(0)
	s_waitcnt lgkmcnt(0)
	s_setprio 1
	s_barrier
	v_mfma_f32_16x16x32_bf16 v[64:67], v[132:135], v[200:203], v[64:67]
	v_mfma_f32_16x16x32_bf16 v[60:63], v[140:143], v[200:203], v[60:63]
	v_mfma_f32_16x16x32_bf16 v[48:51], v[132:135], v[208:211], v[48:51]
	v_mfma_f32_16x16x32_bf16 v[44:47], v[140:143], v[208:211], v[44:47]
	v_mfma_f32_16x16x32_bf16 v[32:35], v[132:135], v[216:219], v[32:35]
	v_mfma_f32_16x16x32_bf16 v[28:31], v[140:143], v[216:219], v[28:31]
	v_mfma_f32_16x16x32_bf16 v[16:19], v[132:135], v[224:227], v[16:19]
	v_mfma_f32_16x16x32_bf16 v[12:15], v[140:143], v[224:227], v[12:15]
	v_mfma_f32_16x16x32_bf16 v[64:67], v[136:139], v[204:207], v[64:67]
	v_mfma_f32_16x16x32_bf16 v[60:63], v[178:181], v[204:207], v[60:63]
	v_mfma_f32_16x16x32_bf16 v[48:51], v[136:139], v[212:215], v[48:51]
	v_mfma_f32_16x16x32_bf16 v[44:47], v[178:181], v[212:215], v[44:47]
	v_mfma_f32_16x16x32_bf16 v[32:35], v[136:139], v[220:223], v[32:35]
	v_mfma_f32_16x16x32_bf16 v[28:31], v[178:181], v[220:223], v[28:31]
	v_mfma_f32_16x16x32_bf16 v[16:19], v[136:139], v[228:231], v[16:19]
	v_mfma_f32_16x16x32_bf16 v[12:15], v[178:181], v[228:231], v[12:15]
	s_setprio 0
	s_setprio 1
	v_mfma_f32_16x16x32_bf16 v[56:59], v[182:185], v[200:203], v[56:59]
	v_mfma_f32_16x16x32_bf16 v[52:55], v[192:195], v[200:203], v[52:55]
	v_mfma_f32_16x16x32_bf16 v[40:43], v[182:185], v[208:211], v[40:43]
	s_or_b64 vcc, s[18:19], s[62:63]
	v_mfma_f32_16x16x32_bf16 v[36:39], v[192:195], v[208:211], v[36:39]
	s_cmp_eq_u32 s2, 16
	v_mfma_f32_16x16x32_bf16 v[24:27], v[182:185], v[216:219], v[24:27]
	s_cselect_b32 s100, 1, 0
	v_mfma_f32_16x16x32_bf16 v[20:23], v[192:195], v[216:219], v[20:23]
	s_cmp_eq_u32 s2, 24
	v_mfma_f32_16x16x32_bf16 v[6:9], v[182:185], v[224:227], v[8:11]
	s_cselect_b32 s101, 1, 0
	v_mfma_f32_16x16x32_bf16 v[2:5], v[192:195], v[224:227], v[2:5]
	s_or_b32 s100, s100, s101
	v_mfma_f32_16x16x32_bf16 v[56:59], v[188:191], v[204:207], v[56:59]
	s_cmp_eq_u64 vcc, 0
	v_mfma_f32_16x16x32_bf16 v[52:55], v[196:199], v[204:207], v[52:55]
	s_cselect_b32 s100, s100, 0
	v_mfma_f32_16x16x32_bf16 v[40:43], v[188:191], v[212:215], v[40:43]
	s_cmp_lg_u32 s100, 0
	v_mfma_f32_16x16x32_bf16 v[36:39], v[196:199], v[212:215], v[36:39]
	v_mfma_f32_16x16x32_bf16 v[24:27], v[188:191], v[220:223], v[24:27]
	v_mfma_f32_16x16x32_bf16 v[20:23], v[196:199], v[220:223], v[20:23]
	v_mfma_f32_16x16x32_bf16 v[8:11], v[188:191], v[228:231], v[6:9]
	v_mfma_f32_16x16x32_bf16 v[4:7], v[196:199], v[228:231], v[2:5]
	s_setprio 0
	s_cbranch_scc0 .Lhk_skipB

.LBB0_671:
	s_add_u32 s6, s6, 0x80080
	s_addc_u32 s7, s7, 0
	s_add_u32 s5, s40, 0x100
	s_addc_u32 s25, s41, 0
	s_mov_b32 s56, -2
	ds_read_b128 v[128:131], v185
	ds_read_b128 v[132:135], v185 offset:1024
	ds_read_b128 v[136:139], v185 offset:2048
	ds_read_b128 v[140:143], v185 offset:3072
	ds_read_b128 v[162:165], v186
	ds_read_b128 v[166:169], v186 offset:1024
	ds_read_b128 v[170:173], v186 offset:2048
	ds_read_b128 v[174:177], v186 offset:3072
	s_add_u32 s38, s6, 0xfff80080
	s_addc_u32 s39, s7, -1
	s_cmp_eq_u32 s56, 28
	s_cselect_b32 s41, s27, s39
	s_cselect_b32 s40, s26, s38
	s_cselect_b32 s39, s23, s25
	s_cselect_b32 s38, s22, s5
	v_lshl_add_u64 v[182:183], s[6:7], 0, v[158:159]
	s_add_i32 m0, s42, 0xc000
	ds_read_b128 v[178:181], v188
	ds_read_b128 v[192:195], v188 offset:1024
	ds_read_b128 v[196:199], v188 offset:2048
	ds_read_b128 v[200:203], v188 offset:3072
	ds_read_b128 v[204:207], v188 offset:4096
	ds_read_b128 v[208:211], v188 offset:5120
	ds_read_b128 v[212:215], v188 offset:6144
	ds_read_b128 v[216:219], v188 offset:7168
	global_load_lds_dwordx4 v[182:183], off
	v_lshl_add_u64 v[182:183], s[6:7], 0, v[160:161]
	s_add_i32 m0, s42, 0xe000
	s_nop 0
	global_load_lds_dwordx4 v[182:183], off
	s_waitcnt vmcnt(8)
	s_waitcnt lgkmcnt(0)
	s_waitcnt lgkmcnt(0)
	s_setprio 1
	s_barrier
	v_mfma_f32_16x16x32_bf16 v[124:127], v[128:131], v[178:181], 0
	v_mfma_f32_16x16x32_bf16 v[120:123], v[136:139], v[178:181], 0
	v_mfma_f32_16x16x32_bf16 v[108:111], v[128:131], v[196:199], 0
	v_mfma_f32_16x16x32_bf16 v[104:107], v[136:139], v[196:199], 0
	v_mfma_f32_16x16x32_bf16 v[92:95], v[128:131], v[204:207], 0
	v_mfma_f32_16x16x32_bf16 v[88:91], v[136:139], v[204:207], 0
	v_mfma_f32_16x16x32_bf16 v[76:79], v[128:131], v[212:215], 0
	v_mfma_f32_16x16x32_bf16 v[72:75], v[136:139], v[212:215], 0
	v_mfma_f32_16x16x32_bf16 v[124:127], v[132:135], v[192:195], v[124:127]
	v_mfma_f32_16x16x32_bf16 v[120:123], v[140:143], v[192:195], v[120:123]
	v_mfma_f32_16x16x32_bf16 v[108:111], v[132:135], v[200:203], v[108:111]
	v_mfma_f32_16x16x32_bf16 v[104:107], v[140:143], v[200:203], v[104:107]
	v_mfma_f32_16x16x32_bf16 v[92:95], v[132:135], v[208:211], v[92:95]
	v_mfma_f32_16x16x32_bf16 v[88:91], v[140:143], v[208:211], v[88:91]
	v_mfma_f32_16x16x32_bf16 v[76:79], v[132:135], v[216:219], v[76:79]
	v_mfma_f32_16x16x32_bf16 v[72:75], v[140:143], v[216:219], v[72:75]
	s_setprio 0
	s_setprio 1
	v_mfma_f32_16x16x32_bf16 v[116:119], v[162:165], v[178:181], 0
	v_mfma_f32_16x16x32_bf16 v[112:115], v[170:173], v[178:181], 0
	v_mfma_f32_16x16x32_bf16 v[100:103], v[162:165], v[196:199], 0
	v_mfma_f32_16x16x32_bf16 v[96:99], v[170:173], v[196:199], 0
	v_mfma_f32_16x16x32_bf16 v[84:87], v[162:165], v[204:207], 0
	v_mfma_f32_16x16x32_bf16 v[80:83], v[170:173], v[204:207], 0
	v_mfma_f32_16x16x32_bf16 v[68:71], v[162:165], v[212:215], 0
	v_mfma_f32_16x16x32_bf16 v[64:67], v[170:173], v[212:215], 0
	v_mfma_f32_16x16x32_bf16 v[116:119], v[166:169], v[192:195], v[116:119]
	v_mfma_f32_16x16x32_bf16 v[112:115], v[174:177], v[192:195], v[112:115]
	v_mfma_f32_16x16x32_bf16 v[100:103], v[166:169], v[200:203], v[100:103]
	v_mfma_f32_16x16x32_bf16 v[96:99], v[174:177], v[200:203], v[96:99]
	v_mfma_f32_16x16x32_bf16 v[84:87], v[166:169], v[208:211], v[84:87]
	v_mfma_f32_16x16x32_bf16 v[80:83], v[174:177], v[208:211], v[80:83]
	v_mfma_f32_16x16x32_bf16 v[68:71], v[166:169], v[216:219], v[68:71]
	v_mfma_f32_16x16x32_bf16 v[64:67], v[174:177], v[216:219], v[64:67]
	s_barrier
	s_setprio 0
	s_add_i32 s57, s51, s35
	v_lshl_add_u64 v[182:183], s[38:39], 0, v[148:149]
	s_mov_b32 m0, s57
	ds_read_b128 v[178:181], v188 offset:16384
	ds_read_b128 v[192:195], v188 offset:17408
	ds_read_b128 v[196:199], v188 offset:18432
	ds_read_b128 v[200:203], v188 offset:19456
	ds_read_b128 v[204:207], v188 offset:20480
	ds_read_b128 v[208:211], v188 offset:21504
	ds_read_b128 v[212:215], v188 offset:22528
	ds_read_b128 v[216:219], v188 offset:23552
	global_load_lds_dwordx4 v[182:183], off
	s_add_i32 m0, s57, 0x2000
	s_add_u32 s58, s38, 0x80000
	v_lshl_add_u64 v[220:221], s[38:39], 0, v[144:145]
	s_addc_u32 s59, s39, 0
	s_add_i32 s57, s52, s35
	global_load_lds_dwordx4 v[220:221], off
	v_lshl_add_u64 v[222:223], s[58:59], 0, v[148:149]
	s_mov_b32 m0, s57
	v_lshl_add_u64 v[224:225], s[40:41], 0, v[146:147]
	global_load_lds_dwordx4 v[222:223], off
	v_lshl_add_u64 v[222:223], s[58:59], 0, v[144:145]
	s_add_i32 m0, s57, 0x2000
	s_nop 0
	global_load_lds_dwordx4 v[222:223], off
	v_lshl_add_u64 v[222:223], s[40:41], 0, v[150:151]
	s_mov_b32 m0, s42
	s_nop 0
	global_load_lds_dwordx4 v[222:223], off
	s_mov_b32 m0, s43
	s_nop 0
	global_load_lds_dwordx4 v[224:225], off
	s_waitcnt vmcnt(8)
	s_waitcnt lgkmcnt(0)
	s_waitcnt lgkmcnt(0)
	s_setprio 1
	s_barrier
	v_mfma_f32_16x16x32_bf16 v[60:63], v[128:131], v[178:181], 0
	v_mfma_f32_16x16x32_bf16 v[56:59], v[136:139], v[178:181], 0
	v_mfma_f32_16x16x32_bf16 v[44:47], v[128:131], v[196:199], 0
	v_mfma_f32_16x16x32_bf16 v[40:43], v[136:139], v[196:199], 0
	v_mfma_f32_16x16x32_bf16 v[28:31], v[128:131], v[204:207], 0
	v_mfma_f32_16x16x32_bf16 v[24:27], v[136:139], v[204:207], 0
	v_mfma_f32_16x16x32_bf16 v[12:15], v[128:131], v[212:215], 0
	v_mfma_f32_16x16x32_bf16 v[8:11], v[136:139], v[212:215], 0
	v_mfma_f32_16x16x32_bf16 v[60:63], v[132:135], v[192:195], v[60:63]
	v_mfma_f32_16x16x32_bf16 v[56:59], v[140:143], v[192:195], v[56:59]
	v_mfma_f32_16x16x32_bf16 v[44:47], v[132:135], v[200:203], v[44:47]
	v_mfma_f32_16x16x32_bf16 v[40:43], v[140:143], v[200:203], v[40:43]
	v_mfma_f32_16x16x32_bf16 v[28:31], v[132:135], v[208:211], v[28:31]
	v_mfma_f32_16x16x32_bf16 v[24:27], v[140:143], v[208:211], v[24:27]
	v_mfma_f32_16x16x32_bf16 v[12:15], v[132:135], v[216:219], v[12:15]
	v_mfma_f32_16x16x32_bf16 v[8:11], v[140:143], v[216:219], v[8:11]
	s_setprio 0
	s_setprio 1
	v_mfma_f32_16x16x32_bf16 v[52:55], v[162:165], v[178:181], 0
	v_mfma_f32_16x16x32_bf16 v[48:51], v[170:173], v[178:181], 0
	v_mfma_f32_16x16x32_bf16 v[36:39], v[162:165], v[196:199], 0
	v_mfma_f32_16x16x32_bf16 v[32:35], v[170:173], v[196:199], 0
	v_mfma_f32_16x16x32_bf16 v[20:23], v[162:165], v[204:207], 0
	v_mfma_f32_16x16x32_bf16 v[16:19], v[170:173], v[204:207], 0
	v_mfma_f32_16x16x32_bf16 v[4:7], v[162:165], v[212:215], 0
	v_mfma_f32_16x16x32_bf16 v[0:3], v[170:173], v[212:215], 0
	v_mfma_f32_16x16x32_bf16 v[52:55], v[166:169], v[192:195], v[52:55]
	v_mfma_f32_16x16x32_bf16 v[48:51], v[174:177], v[192:195], v[48:51]
	v_mfma_f32_16x16x32_bf16 v[36:39], v[166:169], v[200:203], v[36:39]
	v_mfma_f32_16x16x32_bf16 v[32:35], v[174:177], v[200:203], v[32:35]
	v_mfma_f32_16x16x32_bf16 v[20:23], v[166:169], v[208:211], v[20:23]
	v_mfma_f32_16x16x32_bf16 v[16:19], v[174:177], v[208:211], v[16:19]
	v_mfma_f32_16x16x32_bf16 v[4:7], v[166:169], v[216:219], v[4:7]
	v_mfma_f32_16x16x32_bf16 v[0:3], v[174:177], v[216:219], v[0:3]
	s_barrier
	s_setprio 0
	s_branch .Lpeel_mid_p4
	s_nop 0
	s_nop 0
	s_nop 0
	s_nop 0
	s_nop 0
	s_nop 0
	s_nop 0
	s_nop 0
	s_nop 0
	s_nop 0
	s_nop 0
	s_nop 0
	s_nop 0
	s_nop 0
